# v7_stagger_gatelast_wt_nt
# speedup vs baseline: 1.0497x; 1.0007x over previous
.LBB0_873:
	s_mul_i32 s5, s8, s4
	s_sub_i32 s5, s6, s5
	s_ashr_i32 s3, s9, 3
	s_xor_b32 s2, s11, s2
	s_add_i32 s6, s8, 1
	s_sub_i32 s9, s5, s4
	s_cmp_ge_u32 s5, s4
	s_cselect_b32 s6, s6, s8
	s_cselect_b32 s5, s9, s5
	s_add_i32 s8, s6, 1
	s_cmp_ge_u32 s5, s4
	s_cselect_b32 s4, s8, s6
	s_xor_b32 s4, s4, s2
	s_sub_i32 s4, s4, s2
	s_add_i32 s2, s7, s3
	s_ashr_i32 s3, s2, 31
	s_lshr_b32 s3, s3, 26
	s_add_i32 s3, s2, s3
	s_and_b32 s3, s3, 0xffc0
	s_sub_i32 s2, s2, s3
	s_bfe_i32 s3, s2, 0x80000
	s_bfe_u32 s3, s3, 0x3000c
	s_add_i32 s2, s2, s3
	s_bfe_i32 s2, s2, 0x80000
	s_sext_i32_i16 s2, s2
	s_ashr_i32 s2, s2, 3
	s_add_i32 s2, s2, 0xfff9
	s_and_b32 s2, s2, 0xffff
	s_cmpk_ge_u32 s2, 0xfffc
	s_cselect_b64 s[2:3], -1, 0
	s_add_i32 s4, s4, -3
	s_cmp_ge_u32 s4, 4
	s_cselect_b64 s[4:5], -1, 0
	s_and_b64 s[2:3], s[4:5], s[2:3]
	v_cndmask_b32_e64 v0, 0, 1, s[2:3]
	s_nop 0
	v_readfirstlane_b32 s33, v0
